# cache policy: the residual stream's f32 stores in the fused residual epilogue non-temporal (75 MB per phase that nothing re-reads before the next residual phase)
# speedup vs baseline: 1.0067x; 1.0067x over previous
;     __device__ __forceinline__ void fused(f32x4 (&acc)[2][2][4][2], const Unit& u, int wr, int wc, int fr, int fq, ldsp lds, int wid, int lane) const {
;         const int rowt = u.pm * BM, b = rowt >> 11;
;         const char* xsb = (const char*)(xs + (size_t)rowt * D + u.pn * BM);
;         char* xdb = (char*)(xd + (size_t)rowt * D + u.pn * BM);
;         const char* gp = (const char*)(gate + (size_t)b * NMOD + u.pn * BM);
;         const unsigned coff = (unsigned)(wc * 32 + 4 * fq) * 4u;
;         unsigned off0 = (unsigned)(wr * 64 + fr) * (D * 4u) + coff; asm volatile("" : "+v"(off0));
; #pragma unroll
;         for (int bj = 0; bj < 2; ++bj)
; #pragma unroll
;             for (int n = 0; n < 2; ++n) { const f32x4 gv = *(const f32x4*)(gp + coff + (bj * HALF + n * 16) * 4);
; #pragma unroll
;                 for (int ai = 0; ai < 2; ++ai) {
; #pragma unroll
;                     for (int m = 0; m < 4; ++m) { const unsigned off = off0 + (unsigned)((ai * HALF + m * 16) * D + bj * HALF + n * 16) * 4u;
;                         const f32x4 xv = *(const f32x4*)(xsb + off); acc[ai][bj][m][n] = xv + gv * acc[ai][bj][m][n];
;                         if (!fin) *(f32x4*)(xdb + off) = acc[ai][bj][m][n]; }
;                     asm volatile("" ::: "memory"); } }
.LBB0_352:
	v_readlane_b32 s8, v255, 19
	s_lshl_b32 s5, s8, 2
	v_readlane_b32 s8, v254, 30
	s_add_u32 s5, s8, s5
	v_readlane_b32 s8, v254, 31
	v_readlane_b32 s9, v255, 20
	s_addc_u32 s24, s8, 0
	s_lshl_b32 s8, s3, 8
	s_ashr_i32 s9, s8, 31
	s_ashr_i32 s25, s3, 3
	s_lshl_b64 s[10:11], s[8:9], 12
	v_readlane_b32 s12, v254, 32
	v_readlane_b32 s13, v254, 33
	s_add_u32 s9, s12, s10
	s_addc_u32 s12, s13, s11
	s_lshl_b32 s14, s40, 8
	s_ashr_i32 s15, s14, 31
	s_lshl_b64 s[22:23], s[14:15], 2
	s_add_u32 s42, s9, s22
	s_addc_u32 s43, s12, s23
	s_add_u32 s9, s54, s10
	s_addc_u32 s10, s55, s11
	s_add_u32 s12, s9, s22
	s_addc_u32 s13, s10, s23
	s_mul_hi_i32 s11, s25, 0x1800
	s_mul_i32 s10, s25, 0x1800
	s_lshl_b64 s[30:31], s[10:11], 2
	v_lshl_or_b32 v149, s4, 5, v161
	s_add_u32 s5, s5, s30
	v_lshlrev_b32_e32 v146, 2, v149
	s_addc_u32 s9, s24, s31
	v_lshl_or_b32 v96, v148, 12, v146
	s_add_u32 s22, s5, s22
	s_addc_u32 s23, s9, s23
	v_add_u32_e32 v147, 0x10000, v96
	v_add_u32_e32 v194, 0x20000, v96
	v_add_u32_e32 v195, 0x30000, v96
	v_add_u32_e32 v197, 0x80000, v96
	v_add_u32_e32 v198, 0x90000, v96
	v_add_u32_e32 v199, 0xa0000, v96
	v_add_u32_e32 v200, 0xb0000, v96
	global_load_dwordx4 v[142:145], v146, s[22:23]
	global_load_dwordx4 v[150:153], v146, s[22:23] offset:64
	global_load_dwordx4 v[190:193], v146, s[22:23] offset:512
	global_load_dwordx4 v[162:165], v96, s[42:43]
	global_load_dwordx4 v[166:169], v147, s[42:43]
	global_load_dwordx4 v[170:173], v194, s[42:43]
	global_load_dwordx4 v[174:177], v195, s[42:43]
	global_load_dwordx4 v[178:181], v197, s[42:43]
	global_load_dwordx4 v[182:185], v198, s[42:43]
	global_load_dwordx4 v[226:229], v199, s[42:43]
	global_load_dwordx4 v[230:233], v200, s[42:43]
	global_load_dwordx4 v[234:237], v96, s[42:43] offset:64
	global_load_dwordx4 v[238:241], v147, s[42:43] offset:64
	global_load_dwordx4 v[242:245], v194, s[42:43] offset:64
	global_load_dwordx4 v[246:249], v195, s[42:43] offset:64
	global_load_dwordx4 v[250:253], v197, s[42:43] offset:64
	global_load_dwordx4 v[202:205], v198, s[42:43] offset:64
	global_load_dwordx4 v[206:209], v199, s[42:43] offset:64
	global_load_dwordx4 v[210:213], v200, s[42:43] offset:64
	s_waitcnt vmcnt(19)
	s_barrier
	v_cndmask_b32_e64 v134, 0, 1, s[84:85]
	v_cmp_ne_u32_e64 s[10:11], 1, v134
	v_readlane_b32 s36, v255, 14
	v_readlane_b32 s44, v255, 0
	s_mov_b32 s64, 0x41000000
	v_readlane_b32 s65, v254, 51
	v_readlane_b32 s37, v255, 15
	v_readlane_b32 s45, v255, 1
	s_andn2_b64 vcc, exec, s[84:85]
	s_cbranch_vccnz .Lrn_ladder_fin
	s_waitcnt vmcnt(15)
	v_pk_fma_f32 v[140:141], v[128:129], v[144:145], v[164:165]
	v_pk_fma_f32 v[138:139], v[126:127], v[142:143], v[162:163]
	global_store_dwordx4 v96, v[138:141], s[12:13] nt
	global_load_dwordx4 v[162:165], v96, s[42:43] offset:512
	s_waitcnt vmcnt(16)
	v_pk_fma_f32 v[136:137], v[124:125], v[144:145], v[168:169]
	v_pk_fma_f32 v[134:135], v[122:123], v[142:143], v[166:167]
	global_store_dwordx4 v147, v[134:137], s[12:13] nt
	global_load_dwordx4 v[166:169], v147, s[42:43] offset:512
	s_waitcnt vmcnt(17)
	v_pk_fma_f32 v[132:133], v[116:117], v[144:145], v[172:173]
	v_pk_fma_f32 v[130:131], v[114:115], v[142:143], v[170:171]
	global_store_dwordx4 v194, v[130:133], s[12:13] nt
	global_load_dwordx4 v[170:173], v194, s[42:43] offset:512
	s_waitcnt vmcnt(18)
	v_pk_fma_f32 v[128:129], v[108:109], v[144:145], v[176:177]
	v_pk_fma_f32 v[126:127], v[106:107], v[142:143], v[174:175]
	global_store_dwordx4 v195, v[126:129], s[12:13] nt
	global_load_dwordx4 v[174:177], v195, s[42:43] offset:512
	s_waitcnt vmcnt(19)
	v_pk_fma_f32 v[124:125], v[100:101], v[144:145], v[180:181]
	v_pk_fma_f32 v[122:123], v[98:99], v[142:143], v[178:179]
	global_store_dwordx4 v197, v[122:125], s[12:13] nt
	global_load_dwordx4 v[178:181], v197, s[42:43] offset:512
	s_waitcnt vmcnt(20)
	v_pk_fma_f32 v[116:117], v[90:91], v[144:145], v[184:185]
	v_pk_fma_f32 v[114:115], v[88:89], v[142:143], v[182:183]
	global_store_dwordx4 v198, v[114:117], s[12:13] nt
	global_load_dwordx4 v[182:185], v198, s[42:43] offset:512
	s_waitcnt vmcnt(21)
	v_pk_fma_f32 v[108:109], v[82:83], v[144:145], v[228:229]
	v_pk_fma_f32 v[106:107], v[80:81], v[142:143], v[226:227]
	global_store_dwordx4 v199, v[106:109], s[12:13] nt
	global_load_dwordx4 v[226:229], v199, s[42:43] offset:512
	s_waitcnt vmcnt(22)
	v_pk_fma_f32 v[100:101], v[74:75], v[144:145], v[232:233]
	v_pk_fma_f32 v[98:99], v[72:73], v[142:143], v[230:231]
	global_store_dwordx4 v200, v[98:101], s[12:13] nt
	global_load_dwordx4 v[230:233], v200, s[42:43] offset:512
	global_load_dwordx4 v[142:145], v146, s[22:23] offset:576
	s_waitcnt vmcnt(24)
	v_pk_fma_f32 v[94:95], v[94:95], v[152:153], v[236:237]
	v_pk_fma_f32 v[92:93], v[92:93], v[150:151], v[234:235]
	global_store_dwordx4 v96, v[92:95], s[12:13] offset:64 nt
	global_load_dwordx4 v[234:237], v96, s[42:43] offset:576
	s_waitcnt vmcnt(25)
;     __device__ __forceinline__ void fused(f32x4 (&acc)[2][2][4][2], const Unit& u, int wr, int wc, int fr, int fq, ldsp lds, int wid, int lane) const {
;     ...
;             for (int n = 0; n < 2; ++n) { const f32x4 gv = *(const f32x4*)(gp + coff + (bj * HALF + n * 16) * 4);
; #pragma unroll
;                 for (int ai = 0; ai < 2; ++ai) {
; #pragma unroll
;                     for (int m = 0; m < 4; ++m) { const unsigned off = off0 + (unsigned)((ai * HALF + m * 16) * D + bj * HALF + n * 16) * 4u;
;                         const f32x4 xv = *(const f32x4*)(xsb + off); acc[ai][bj][m][n] = xv + gv * acc[ai][bj][m][n];
;                         if (!fin) *(f32x4*)(xdb + off) = acc[ai][bj][m][n]; }
;                     asm volatile("" ::: "memory"); } }
	v_pk_fma_f32 v[90:91], v[86:87], v[152:153], v[240:241]
	v_pk_fma_f32 v[88:89], v[84:85], v[150:151], v[238:239]
	global_store_dwordx4 v147, v[88:91], s[12:13] offset:64 nt
	global_load_dwordx4 v[238:241], v147, s[42:43] offset:576
	s_waitcnt vmcnt(26)
	v_pk_fma_f32 v[86:87], v[78:79], v[152:153], v[244:245]
	v_pk_fma_f32 v[84:85], v[76:77], v[150:151], v[242:243]
	global_store_dwordx4 v194, v[84:87], s[12:13] offset:64 nt
	global_load_dwordx4 v[242:245], v194, s[42:43] offset:576
	s_waitcnt vmcnt(27)
	v_pk_fma_f32 v[82:83], v[70:71], v[152:153], v[248:249]
	v_pk_fma_f32 v[80:81], v[68:69], v[150:151], v[246:247]
	global_store_dwordx4 v195, v[80:83], s[12:13] offset:64 nt
	global_load_dwordx4 v[246:249], v195, s[42:43] offset:576
	s_waitcnt vmcnt(28)
	v_pk_fma_f32 v[78:79], v[66:67], v[152:153], v[252:253]
	v_pk_fma_f32 v[76:77], v[64:65], v[150:151], v[250:251]
	global_store_dwordx4 v197, v[76:79], s[12:13] offset:64 nt
	global_load_dwordx4 v[250:253], v197, s[42:43] offset:576
	s_waitcnt vmcnt(29)
	v_pk_fma_f32 v[74:75], v[62:63], v[152:153], v[204:205]
	v_pk_fma_f32 v[72:73], v[60:61], v[150:151], v[202:203]
	global_store_dwordx4 v198, v[72:75], s[12:13] offset:64 nt
	global_load_dwordx4 v[202:205], v198, s[42:43] offset:576
	s_waitcnt vmcnt(30)
	v_pk_fma_f32 v[70:71], v[54:55], v[152:153], v[208:209]
	v_pk_fma_f32 v[68:69], v[52:53], v[150:151], v[206:207]
	global_store_dwordx4 v199, v[68:71], s[12:13] offset:64 nt
	global_load_dwordx4 v[206:209], v199, s[42:43] offset:576
	s_waitcnt vmcnt(31)
	v_pk_fma_f32 v[66:67], v[46:47], v[152:153], v[212:213]
	v_pk_fma_f32 v[64:65], v[44:45], v[150:151], v[210:211]
	global_store_dwordx4 v200, v[64:67], s[12:13] offset:64 nt
	global_load_dwordx4 v[210:213], v200, s[42:43] offset:576
	s_waitcnt vmcnt(31)
	v_pk_fma_f32 v[62:63], v[58:59], v[192:193], v[164:165]
	v_pk_fma_f32 v[60:61], v[56:57], v[190:191], v[162:163]
	global_store_dwordx4 v96, v[60:63], s[12:13] offset:512 nt
	s_waitcnt vmcnt(30)
	v_pk_fma_f32 v[58:59], v[50:51], v[192:193], v[168:169]
	v_pk_fma_f32 v[56:57], v[48:49], v[190:191], v[166:167]
	global_store_dwordx4 v147, v[56:59], s[12:13] offset:512 nt
	s_waitcnt vmcnt(29)
	v_pk_fma_f32 v[54:55], v[42:43], v[192:193], v[172:173]
	v_pk_fma_f32 v[52:53], v[40:41], v[190:191], v[170:171]
	global_store_dwordx4 v194, v[52:55], s[12:13] offset:512 nt
	s_waitcnt vmcnt(28)
	v_pk_fma_f32 v[50:51], v[38:39], v[192:193], v[176:177]
	v_pk_fma_f32 v[48:49], v[36:37], v[190:191], v[174:175]
	global_store_dwordx4 v195, v[48:51], s[12:13] offset:512 nt
	s_waitcnt vmcnt(27)
	v_pk_fma_f32 v[46:47], v[34:35], v[192:193], v[180:181]
	v_pk_fma_f32 v[44:45], v[32:33], v[190:191], v[178:179]
	global_store_dwordx4 v197, v[44:47], s[12:13] offset:512 nt
	s_waitcnt vmcnt(26)
	v_pk_fma_f32 v[42:43], v[30:31], v[192:193], v[184:185]
	v_pk_fma_f32 v[40:41], v[28:29], v[190:191], v[182:183]
	global_store_dwordx4 v198, v[40:43], s[12:13] offset:512 nt
	s_waitcnt vmcnt(25)
	v_pk_fma_f32 v[38:39], v[26:27], v[192:193], v[228:229]
	v_pk_fma_f32 v[36:37], v[24:25], v[190:191], v[226:227]
	global_store_dwordx4 v199, v[36:39], s[12:13] offset:512 nt
	s_waitcnt vmcnt(24)
	v_pk_fma_f32 v[34:35], v[22:23], v[192:193], v[232:233]
	v_pk_fma_f32 v[32:33], v[20:21], v[190:191], v[230:231]
	global_store_dwordx4 v200, v[32:35], s[12:13] offset:512 nt
	s_waitcnt vmcnt(22)
	v_pk_fma_f32 v[30:31], v[120:121], v[144:145], v[236:237]
	v_pk_fma_f32 v[28:29], v[118:119], v[142:143], v[234:235]
	global_store_dwordx4 v96, v[28:31], s[12:13] offset:576 nt
	s_waitcnt vmcnt(21)
	v_pk_fma_f32 v[26:27], v[112:113], v[144:145], v[240:241]
	v_pk_fma_f32 v[24:25], v[110:111], v[142:143], v[238:239]
	global_store_dwordx4 v147, v[24:27], s[12:13] offset:576 nt
	s_waitcnt vmcnt(20)
	v_pk_fma_f32 v[22:23], v[104:105], v[144:145], v[244:245]
	v_pk_fma_f32 v[20:21], v[102:103], v[142:143], v[242:243]
	global_store_dwordx4 v194, v[20:23], s[12:13] offset:576 nt
	s_waitcnt vmcnt(19)
	v_pk_fma_f32 v[18:19], v[18:19], v[144:145], v[248:249]
	v_pk_fma_f32 v[16:17], v[16:17], v[142:143], v[246:247]
	global_store_dwordx4 v195, v[16:19], s[12:13] offset:576 nt
	s_waitcnt vmcnt(18)
	v_pk_fma_f32 v[14:15], v[14:15], v[144:145], v[252:253]
	v_pk_fma_f32 v[12:13], v[12:13], v[142:143], v[250:251]
	global_store_dwordx4 v197, v[12:15], s[12:13] offset:576 nt
	s_waitcnt vmcnt(17)
	v_pk_fma_f32 v[10:11], v[10:11], v[144:145], v[204:205]
	v_pk_fma_f32 v[8:9], v[8:9], v[142:143], v[202:203]
	global_store_dwordx4 v198, v[8:11], s[12:13] offset:576 nt
	s_waitcnt vmcnt(16)
	v_pk_fma_f32 v[6:7], v[6:7], v[144:145], v[208:209]
	v_pk_fma_f32 v[4:5], v[4:5], v[142:143], v[206:207]
	global_store_dwordx4 v199, v[4:7], s[12:13] offset:576 nt
	s_waitcnt vmcnt(15)
	v_pk_fma_f32 v[2:3], v[2:3], v[144:145], v[212:213]
	v_pk_fma_f32 v[0:1], v[0:1], v[142:143], v[210:211]
	global_store_dwordx4 v200, v[0:3], s[12:13] offset:576 nt
	s_branch .Lrn_ladder_done
